# NSA edge tiles (diagonal / window boundary): interior-tile code with one compare+select per score (-inf mask) instead of the 2-trip half loop on accumulator copies
# baseline (speedup 1.0000x reference)
.LBB0_289:
	v_and_b32_e32 v173, 31, v133
	v_bfe_u32 v213, v133, 5, 1
	v_lshlrev_b32_e32 v213, 3, v213
	v_sub_u32_e32 v173, v173, v213
	s_sub_i32 s4, s8, s15
	v_add_u32_e32 v173, s4, v173
	v_add_u32_e32 v213, 0xffffffe0, v173
	v_mov_b32_e32 v174, 0xff800000
	v_mad_u32_u24 v0, v217, s37, v3
	v_lshl_add_u32 v215, v156, 1, v3
	ds_read_b128 v[220:223], v0
	ds_read_b128 v[236:239], v0 offset:4608
	ds_read_b128 v[224:227], v0 offset:32
	ds_read_b128 v[240:243], v0 offset:4640
	ds_read_b128 v[228:231], v0 offset:64
	ds_read_b128 v[244:247], v0 offset:4672
	ds_read_b128 v[232:235], v0 offset:96
	ds_read_b128 v[248:251], v0 offset:4704
	ds_read_b128 v[64:67], v215 offset:9216
	ds_read_b128 v[68:71], v215 offset:13824
	ds_read_b128 v[72:75], v215 offset:9248
	ds_read_b128 v[76:79], v215 offset:13856
	s_waitcnt lgkmcnt(11)
	v_mfma_f32_32x32x16_bf16 v[80:95], v[220:223], v[96:99], 0
	s_waitcnt lgkmcnt(10)
	v_mfma_f32_32x32x16_bf16 v[48:63], v[236:239], v[96:99], 0
	s_waitcnt lgkmcnt(9)
	v_mfma_f32_32x32x16_bf16 v[80:95], v[224:227], v[100:103], v[80:95]
	s_waitcnt lgkmcnt(8)
	v_mfma_f32_32x32x16_bf16 v[48:63], v[240:243], v[100:103], v[48:63]
	s_waitcnt lgkmcnt(7)
	v_mfma_f32_32x32x16_bf16 v[80:95], v[228:231], v[104:107], v[80:95]
	s_waitcnt lgkmcnt(6)
	v_mfma_f32_32x32x16_bf16 v[48:63], v[244:247], v[104:107], v[48:63]
	s_waitcnt lgkmcnt(5)
	v_mfma_f32_32x32x16_bf16 v[80:95], v[232:235], v[108:111], v[80:95]
	s_waitcnt lgkmcnt(4)
	v_mfma_f32_32x32x16_bf16 v[48:63], v[248:251], v[108:111], v[48:63]
	ds_read_b128 v[220:223], v215 offset:9280
	ds_read_b128 v[224:227], v215 offset:13888
	ds_read_b128 v[228:231], v215 offset:9312
	ds_read_b128 v[232:235], v215 offset:13920
	s_nop 7
	s_nop 3
	v_cmp_le_i32_e64 vcc, 0, v173
	v_cmp_le_i32_e64 s[4:5], 1, v173
	v_cmp_le_i32_e64 s[6:7], 2, v173
	v_cndmask_b32_e32 v80, v174, v80, vcc
	v_cmp_le_i32_e64 vcc, 3, v173
	v_cndmask_b32_e64 v81, v174, v81, s[4:5]
	v_cmp_le_i32_e64 s[4:5], 4, v173
	v_cndmask_b32_e64 v82, v174, v82, s[6:7]
	v_cmp_le_i32_e64 s[6:7], 5, v173
	v_cndmask_b32_e32 v83, v174, v83, vcc
	v_cmp_le_i32_e64 vcc, 6, v173
	v_cndmask_b32_e64 v84, v174, v84, s[4:5]
	v_cmp_le_i32_e64 s[4:5], 7, v173
	v_cndmask_b32_e64 v85, v174, v85, s[6:7]
	v_cmp_le_i32_e64 s[6:7], 16, v173
	v_cndmask_b32_e32 v86, v174, v86, vcc
	v_cmp_le_i32_e64 vcc, 17, v173
	v_cndmask_b32_e64 v87, v174, v87, s[4:5]
	v_cmp_le_i32_e64 s[4:5], 18, v173
	v_cndmask_b32_e64 v88, v174, v88, s[6:7]
	v_cmp_le_i32_e64 s[6:7], 19, v173
	v_cndmask_b32_e32 v89, v174, v89, vcc
	v_cmp_le_i32_e64 vcc, 20, v173
	v_cndmask_b32_e64 v90, v174, v90, s[4:5]
	v_cmp_le_i32_e64 s[4:5], 21, v173
	v_cndmask_b32_e64 v91, v174, v91, s[6:7]
	v_cmp_le_i32_e64 s[6:7], 22, v173
	v_cndmask_b32_e32 v92, v174, v92, vcc
	v_cmp_le_i32_e64 vcc, 23, v173
	v_cndmask_b32_e64 v93, v174, v93, s[4:5]
	v_cmp_le_i32_e64 s[4:5], 0, v213
	v_cndmask_b32_e64 v94, v174, v94, s[6:7]
	v_cmp_le_i32_e64 s[6:7], 1, v213
	v_cndmask_b32_e32 v95, v174, v95, vcc
	v_cmp_le_i32_e64 vcc, 2, v213
	v_cndmask_b32_e64 v48, v174, v48, s[4:5]
	v_cmp_le_i32_e64 s[4:5], 3, v213
	v_cndmask_b32_e64 v49, v174, v49, s[6:7]
	v_cmp_le_i32_e64 s[6:7], 4, v213
	v_cndmask_b32_e32 v50, v174, v50, vcc
	v_cmp_le_i32_e64 vcc, 5, v213
	v_cndmask_b32_e64 v51, v174, v51, s[4:5]
	v_cmp_le_i32_e64 s[4:5], 6, v213
	v_cndmask_b32_e64 v52, v174, v52, s[6:7]
	v_cmp_le_i32_e64 s[6:7], 7, v213
	v_cndmask_b32_e32 v53, v174, v53, vcc
	v_cmp_le_i32_e64 vcc, 16, v213
	v_cndmask_b32_e64 v54, v174, v54, s[4:5]
	v_cmp_le_i32_e64 s[4:5], 17, v213
	v_cndmask_b32_e64 v55, v174, v55, s[6:7]
	v_cmp_le_i32_e64 s[6:7], 18, v213
	v_cndmask_b32_e32 v56, v174, v56, vcc
	v_cmp_le_i32_e64 vcc, 19, v213
	v_cndmask_b32_e64 v57, v174, v57, s[4:5]
	v_cmp_le_i32_e64 s[4:5], 20, v213
	v_cndmask_b32_e64 v58, v174, v58, s[6:7]
	v_cmp_le_i32_e64 s[6:7], 21, v213
	v_cndmask_b32_e32 v59, v174, v59, vcc
	v_cmp_le_i32_e64 vcc, 22, v213
	v_cndmask_b32_e64 v60, v174, v60, s[4:5]
	v_cmp_le_i32_e64 s[4:5], 23, v213
	v_cndmask_b32_e64 v61, v174, v61, s[6:7]
	s_nop 0
	v_cndmask_b32_e32 v62, v174, v62, vcc
	s_nop 0
	v_cndmask_b32_e64 v63, v174, v63, s[4:5]
	s_nop 0
	v_max3_f32 v0, v80, v81, v82
	v_max3_f32 v2, v88, v89, v90
	v_max3_f32 v0, v0, v83, v84
	v_max3_f32 v2, v2, v91, v92
	v_max3_f32 v0, v0, v85, v86
	v_max3_f32 v2, v2, v93, v94
	v_max3_f32 v0, v0, v87, v95
	v_max_f32_e32 v0, v0, v2
	v_max3_f32 v175, v48, v49, v50
	v_max3_f32 v214, v56, v57, v58
	v_max3_f32 v175, v175, v51, v52
	v_max3_f32 v214, v214, v59, v60
	v_max3_f32 v175, v175, v53, v54
	v_max3_f32 v214, v214, v61, v62
	v_max3_f32 v175, v175, v55, v63
	v_max_f32_e32 v175, v175, v214
	v_cmp_gt_f32_e32 vcc, v0, v219
	s_andn2_b64 vcc, vcc, s[38:39]
	s_cmp_eq_u64 vcc, 0
	s_cbranch_scc1 .Lnsweh_keep0
	v_cndmask_b32_e64 v0, v0, v202, s[38:39]
	s_nop 0
	ds_bpermute_b32 v2, v119, v0
	s_waitcnt lgkmcnt(0)
	v_max_f32_e32 v0, v0, v2
	v_max_f32_e32 v173, v167, v0
	v_sub_f32_e32 v0, v167, v173
	v_exp_f32_e32 v0, v0
	v_mov_b32_e32 v167, v173
	v_add_f32_e32 v219, 0x41200000, v173
	v_mul_f32_e32 v169, v169, v0
	v_pk_mul_f32 v[46:47], v[46:47], v[0:1] op_sel_hi:[1,0]
	v_pk_mul_f32 v[44:45], v[44:45], v[0:1] op_sel_hi:[1,0]
	v_pk_mul_f32 v[42:43], v[42:43], v[0:1] op_sel_hi:[1,0]
	v_pk_mul_f32 v[40:41], v[40:41], v[0:1] op_sel_hi:[1,0]
	v_pk_mul_f32 v[38:39], v[38:39], v[0:1] op_sel_hi:[1,0]
	v_pk_mul_f32 v[36:37], v[36:37], v[0:1] op_sel_hi:[1,0]
	v_pk_mul_f32 v[34:35], v[34:35], v[0:1] op_sel_hi:[1,0]
	v_pk_mul_f32 v[32:33], v[32:33], v[0:1] op_sel_hi:[1,0]
	v_pk_mul_f32 v[30:31], v[30:31], v[0:1] op_sel_hi:[1,0]
	v_pk_mul_f32 v[28:29], v[28:29], v[0:1] op_sel_hi:[1,0]
	v_pk_mul_f32 v[26:27], v[26:27], v[0:1] op_sel_hi:[1,0]
	v_pk_mul_f32 v[24:25], v[24:25], v[0:1] op_sel_hi:[1,0]
	v_pk_mul_f32 v[22:23], v[22:23], v[0:1] op_sel_hi:[1,0]
	v_pk_mul_f32 v[20:21], v[20:21], v[0:1] op_sel_hi:[1,0]
	v_pk_mul_f32 v[18:19], v[18:19], v[0:1] op_sel_hi:[1,0]
	v_pk_mul_f32 v[16:17], v[16:17], v[0:1] op_sel_hi:[1,0]

.Lnsweh_keep1:
	v_cndmask_b32_e64 v174, v167, v206, s[38:39]
	v_sub_f32_e32 v48, v48, v174
	v_exp_f32_e32 v48, v48
	v_sub_f32_e32 v49, v49, v174
	v_exp_f32_e32 v49, v49
	v_sub_f32_e32 v50, v50, v174
	v_exp_f32_e32 v50, v50
	v_add_f32_e32 v213, v49, v48
	v_sub_f32_e32 v51, v51, v174
	v_exp_f32_e32 v51, v51
	v_add_f32_e32 v213, v50, v213
	v_cvt_pk_bf16_f32 v80, v48, v49
	v_sub_f32_e32 v52, v52, v174
	v_exp_f32_e32 v52, v52
	v_add_f32_e32 v213, v51, v213
	v_sub_f32_e32 v53, v53, v174
	v_exp_f32_e32 v53, v53
	v_add_f32_e32 v213, v52, v213
	v_cvt_pk_bf16_f32 v81, v50, v51
	v_sub_f32_e32 v54, v54, v174
	v_exp_f32_e32 v54, v54
	v_add_f32_e32 v213, v53, v213
	v_sub_f32_e32 v55, v55, v174
	v_exp_f32_e32 v55, v55
	v_add_f32_e32 v213, v54, v213
	v_cvt_pk_bf16_f32 v82, v52, v53
	v_sub_f32_e32 v56, v56, v174
	v_exp_f32_e32 v56, v56
	v_add_f32_e32 v213, v55, v213
	v_sub_f32_e32 v57, v57, v174
	v_exp_f32_e32 v57, v57
	v_add_f32_e32 v213, v56, v213
	v_cvt_pk_bf16_f32 v83, v54, v55
	v_sub_f32_e32 v58, v58, v174
	v_exp_f32_e32 v58, v58
	v_add_f32_e32 v213, v57, v213
	s_waitcnt lgkmcnt(3)
	v_mfma_f32_32x32x16_bf16 v[32:47], v[220:223], v[80:83], v[32:47]
	s_waitcnt lgkmcnt(2)
	v_mfma_f32_32x32x16_bf16 v[16:31], v[224:227], v[80:83], v[16:31]
	v_sub_f32_e32 v59, v59, v174
	v_exp_f32_e32 v59, v59
	v_add_f32_e32 v213, v58, v213
	v_cvt_pk_bf16_f32 v84, v56, v57
	v_sub_f32_e32 v60, v60, v174
	v_exp_f32_e32 v60, v60
	v_add_f32_e32 v213, v59, v213
	v_sub_f32_e32 v61, v61, v174
	v_exp_f32_e32 v61, v61
	v_add_f32_e32 v213, v60, v213
	v_cvt_pk_bf16_f32 v85, v58, v59
	v_sub_f32_e32 v62, v62, v174
	v_exp_f32_e32 v62, v62
	v_add_f32_e32 v213, v61, v213
	v_sub_f32_e32 v63, v63, v174
	v_exp_f32_e32 v63, v63
	v_add_f32_e32 v213, v62, v213
	v_cvt_pk_bf16_f32 v86, v60, v61
	v_add_f32_e32 v213, v63, v213
	v_cvt_pk_bf16_f32 v87, v62, v63
	v_add_f32_e32 v169, v169, v213
	s_nop 0
	s_waitcnt lgkmcnt(1)
	v_mfma_f32_32x32x16_bf16 v[32:47], v[228:231], v[84:87], v[32:47]
	s_waitcnt lgkmcnt(0)
	v_mfma_f32_32x32x16_bf16 v[16:31], v[232:235], v[84:87], v[16:31]
.LBB0_296:
	s_xor_b32 s4, s14, 1
	s_mulk_i32 s4, 0x4800
	v_lshl_add_u32 v0, v166, 1, s4
	v_lshl_add_u32 v3, v168, 1, s4
	s_cmp_lg_u32 s12, s10
	s_waitcnt vmcnt(3)
	ds_write_b128 v0, v[8:11]
	s_waitcnt vmcnt(2)
	ds_write_b128 v3, v[4:7]
	s_waitcnt vmcnt(1)
	ds_write_b128 v0, v[12:15] offset:9216
	s_waitcnt vmcnt(0)
	ds_write_b128 v3, v[112:115] offset:9216
	s_waitcnt lgkmcnt(0)
	s_barrier
	s_cbranch_scc0 .Lnsw_exit
	s_mov_b32 s12, s13
	s_branch .LBB0_283

.LBB0_301:
	s_add_i32 s13, s12, 1
	s_min_i32 s4, s13, s10
	s_lshl_b32 s4, s4, 6
	s_ashr_i32 s5, s4, 31
	s_lshl_b64 s[6:7], s[4:5], 7
	s_lshl_b64 s[4:5], s[4:5], 1
	v_lshl_add_u64 v[14:15], v[190:191], 0, s[6:7]
	v_lshl_add_u64 v[10:11], v[164:165], 0, s[4:5]
	global_load_dwordx4 v[6:9], v[14:15], off offset:-2048
	s_nop 0
	global_load_dwordx4 v[2:5], v[14:15], off offset:2048
	v_lshl_add_u64 v[14:15], v[166:167], 0, s[4:5]
	global_load_dwordx4 v[10:13], v[10:11], off
	s_nop 0
	global_load_dwordx4 v[112:115], v[14:15], off
	s_sub_i32 s4, s12, s11
	s_lshl_b32 s6, s12, 6
	s_and_b32 s14, s4, 1
	s_or_b32 s4, s6, 63
	s_cmp_le_i32 s4, s8
	s_cselect_b64 s[4:5], -1, 0
	s_cmp_gt_i32 s6, s9
	s_mul_i32 s7, s14, 0x4800
	s_cselect_b64 s[16:17], -1, 0
	s_and_b64 s[16:17], s[4:5], s[16:17]
	v_or_b32_e32 v14, s7, v129
	s_mov_b64 s[4:5], -1
	s_and_b64 vcc, exec, s[16:17]
	v_add_u32_e32 v15, v14, v161
	s_cbranch_vccnz .LBB0_307
	s_cmp_le_i32 s6, s9
	s_cbranch_scc1 .Lnsw1_elo
	v_and_b32_e32 v173, 31, v133
	v_bfe_u32 v213, v133, 5, 1
	v_lshlrev_b32_e32 v213, 3, v213
	v_sub_u32_e32 v173, v173, v213
	s_sub_i32 s4, s8, s6
	v_add_u32_e32 v173, s4, v173
	v_add_u32_e32 v213, 0xffffffe0, v173
	v_mov_b32_e32 v174, 0xff800000
	v_mad_u32_u24 v0, v218, s37, v14
	v_lshl_add_u32 v215, v159, 1, v14
	ds_read_b128 v[220:223], v0
	ds_read_b128 v[236:239], v0 offset:4608
	ds_read_b128 v[224:227], v0 offset:32
	ds_read_b128 v[240:243], v0 offset:4640
	ds_read_b128 v[228:231], v0 offset:64
	ds_read_b128 v[244:247], v0 offset:4672
	ds_read_b128 v[232:235], v0 offset:96
	ds_read_b128 v[248:251], v0 offset:4704
	ds_read_b128 v[64:67], v215 offset:9216
	ds_read_b128 v[68:71], v215 offset:13824
	ds_read_b128 v[72:75], v215 offset:9248
	ds_read_b128 v[76:79], v215 offset:13856
	s_waitcnt lgkmcnt(11)
	v_mfma_f32_32x32x16_bf16 v[80:95], v[220:223], v[96:99], 0
	s_waitcnt lgkmcnt(10)
	v_mfma_f32_32x32x16_bf16 v[48:63], v[236:239], v[96:99], 0
	s_waitcnt lgkmcnt(9)
	v_mfma_f32_32x32x16_bf16 v[80:95], v[224:227], v[100:103], v[80:95]
	s_waitcnt lgkmcnt(8)
	v_mfma_f32_32x32x16_bf16 v[48:63], v[240:243], v[100:103], v[48:63]
	s_waitcnt lgkmcnt(7)
	v_mfma_f32_32x32x16_bf16 v[80:95], v[228:231], v[104:107], v[80:95]
	s_waitcnt lgkmcnt(6)
	v_mfma_f32_32x32x16_bf16 v[48:63], v[244:247], v[104:107], v[48:63]
	s_waitcnt lgkmcnt(5)
	v_mfma_f32_32x32x16_bf16 v[80:95], v[232:235], v[108:111], v[80:95]
	s_waitcnt lgkmcnt(4)
	v_mfma_f32_32x32x16_bf16 v[48:63], v[248:251], v[108:111], v[48:63]
	ds_read_b128 v[220:223], v215 offset:9280
	ds_read_b128 v[224:227], v215 offset:13888
	ds_read_b128 v[228:231], v215 offset:9312
	ds_read_b128 v[232:235], v215 offset:13920
	s_nop 7
	s_nop 3
	v_cmp_le_i32_e64 vcc, 0, v173
	v_cmp_le_i32_e64 s[4:5], 1, v173
	v_cmp_le_i32_e64 s[6:7], 2, v173
	v_cndmask_b32_e32 v80, v174, v80, vcc
	v_cmp_le_i32_e64 vcc, 3, v173
	v_cndmask_b32_e64 v81, v174, v81, s[4:5]
	v_cmp_le_i32_e64 s[4:5], 4, v173
	v_cndmask_b32_e64 v82, v174, v82, s[6:7]
	v_cmp_le_i32_e64 s[6:7], 5, v173
	v_cndmask_b32_e32 v83, v174, v83, vcc
	v_cmp_le_i32_e64 vcc, 6, v173
	v_cndmask_b32_e64 v84, v174, v84, s[4:5]
	v_cmp_le_i32_e64 s[4:5], 7, v173
	v_cndmask_b32_e64 v85, v174, v85, s[6:7]
	v_cmp_le_i32_e64 s[6:7], 16, v173
	v_cndmask_b32_e32 v86, v174, v86, vcc
	v_cmp_le_i32_e64 vcc, 17, v173
	v_cndmask_b32_e64 v87, v174, v87, s[4:5]
	v_cmp_le_i32_e64 s[4:5], 18, v173
	v_cndmask_b32_e64 v88, v174, v88, s[6:7]
	v_cmp_le_i32_e64 s[6:7], 19, v173
	v_cndmask_b32_e32 v89, v174, v89, vcc
	v_cmp_le_i32_e64 vcc, 20, v173
	v_cndmask_b32_e64 v90, v174, v90, s[4:5]
	v_cmp_le_i32_e64 s[4:5], 21, v173
	v_cndmask_b32_e64 v91, v174, v91, s[6:7]
	v_cmp_le_i32_e64 s[6:7], 22, v173
	v_cndmask_b32_e32 v92, v174, v92, vcc
	v_cmp_le_i32_e64 vcc, 23, v173
	v_cndmask_b32_e64 v93, v174, v93, s[4:5]
	v_cmp_le_i32_e64 s[4:5], 0, v213
	v_cndmask_b32_e64 v94, v174, v94, s[6:7]
	v_cmp_le_i32_e64 s[6:7], 1, v213
	v_cndmask_b32_e32 v95, v174, v95, vcc
	v_cmp_le_i32_e64 vcc, 2, v213
	v_cndmask_b32_e64 v48, v174, v48, s[4:5]
	v_cmp_le_i32_e64 s[4:5], 3, v213
	v_cndmask_b32_e64 v49, v174, v49, s[6:7]
	v_cmp_le_i32_e64 s[6:7], 4, v213
	v_cndmask_b32_e32 v50, v174, v50, vcc
	v_cmp_le_i32_e64 vcc, 5, v213
	v_cndmask_b32_e64 v51, v174, v51, s[4:5]
	v_cmp_le_i32_e64 s[4:5], 6, v213
	v_cndmask_b32_e64 v52, v174, v52, s[6:7]
	v_cmp_le_i32_e64 s[6:7], 7, v213
	v_cndmask_b32_e32 v53, v174, v53, vcc
	v_cmp_le_i32_e64 vcc, 16, v213
	v_cndmask_b32_e64 v54, v174, v54, s[4:5]
	v_cmp_le_i32_e64 s[4:5], 17, v213
	v_cndmask_b32_e64 v55, v174, v55, s[6:7]
	v_cmp_le_i32_e64 s[6:7], 18, v213
	v_cndmask_b32_e32 v56, v174, v56, vcc
	v_cmp_le_i32_e64 vcc, 19, v213
	v_cndmask_b32_e64 v57, v174, v57, s[4:5]
	v_cmp_le_i32_e64 s[4:5], 20, v213
	v_cndmask_b32_e64 v58, v174, v58, s[6:7]
	v_cmp_le_i32_e64 s[6:7], 21, v213
	v_cndmask_b32_e32 v59, v174, v59, vcc
	v_cmp_le_i32_e64 vcc, 22, v213
	v_cndmask_b32_e64 v60, v174, v60, s[4:5]
	v_cmp_le_i32_e64 s[4:5], 23, v213
	v_cndmask_b32_e64 v61, v174, v61, s[6:7]
	s_nop 0
	v_cndmask_b32_e32 v62, v174, v62, vcc
	s_nop 0
	v_cndmask_b32_e64 v63, v174, v63, s[4:5]
	s_nop 0
	v_max3_f32 v0, v80, v81, v82
	v_max3_f32 v216, v88, v89, v90
	v_max3_f32 v0, v0, v83, v84
	v_max3_f32 v216, v216, v91, v92
	v_max3_f32 v0, v0, v85, v86
	v_max3_f32 v216, v216, v93, v94
	v_max3_f32 v0, v0, v87, v95
	v_max_f32_e32 v0, v0, v216
	v_max3_f32 v175, v48, v49, v50
	v_max3_f32 v214, v56, v57, v58
	v_max3_f32 v175, v175, v51, v52
	v_max3_f32 v214, v214, v59, v60
	v_max3_f32 v175, v175, v53, v54
	v_max3_f32 v214, v214, v61, v62
	v_max3_f32 v175, v175, v55, v63
	v_max_f32_e32 v175, v175, v214
	v_cmp_gt_f32_e32 vcc, v0, v219
	s_cmp_eq_u64 vcc, 0
	s_cbranch_scc1 .Lnsw1eh_keep0
	s_nop 0
	ds_bpermute_b32 v216, v119, v0
	s_waitcnt lgkmcnt(0)
	v_max_f32_e32 v0, v0, v216
	v_max_f32_e32 v173, v168, v0
	v_sub_f32_e32 v0, v168, v173
	v_exp_f32_e32 v0, v0
	v_mov_b32_e32 v168, v173
	v_add_f32_e32 v219, 0x41200000, v173
	v_mul_f32_e32 v169, v169, v0
	v_pk_mul_f32 v[46:47], v[46:47], v[0:1] op_sel_hi:[1,0]
	v_pk_mul_f32 v[44:45], v[44:45], v[0:1] op_sel_hi:[1,0]
	v_pk_mul_f32 v[42:43], v[42:43], v[0:1] op_sel_hi:[1,0]
	v_pk_mul_f32 v[40:41], v[40:41], v[0:1] op_sel_hi:[1,0]
	v_pk_mul_f32 v[38:39], v[38:39], v[0:1] op_sel_hi:[1,0]
	v_pk_mul_f32 v[36:37], v[36:37], v[0:1] op_sel_hi:[1,0]
	v_pk_mul_f32 v[34:35], v[34:35], v[0:1] op_sel_hi:[1,0]
	v_pk_mul_f32 v[32:33], v[32:33], v[0:1] op_sel_hi:[1,0]
	v_pk_mul_f32 v[30:31], v[30:31], v[0:1] op_sel_hi:[1,0]
	v_pk_mul_f32 v[28:29], v[28:29], v[0:1] op_sel_hi:[1,0]
	v_pk_mul_f32 v[26:27], v[26:27], v[0:1] op_sel_hi:[1,0]
	v_pk_mul_f32 v[24:25], v[24:25], v[0:1] op_sel_hi:[1,0]
	v_pk_mul_f32 v[22:23], v[22:23], v[0:1] op_sel_hi:[1,0]
	v_pk_mul_f32 v[20:21], v[20:21], v[0:1] op_sel_hi:[1,0]
	v_pk_mul_f32 v[18:19], v[18:19], v[0:1] op_sel_hi:[1,0]
	v_pk_mul_f32 v[16:17], v[16:17], v[0:1] op_sel_hi:[1,0]

.Lnsw1_elo:
	v_and_b32_e32 v173, 31, v133
	v_bfe_u32 v213, v133, 5, 1
	v_lshlrev_b32_e32 v213, 3, v213
	v_sub_u32_e32 v173, v173, v213
	s_sub_i32 s4, s8, s6
	s_addk_i32 s4, 0xfe00
	v_add_u32_e32 v173, s4, v173
	v_add_u32_e32 v213, 0xffffffe0, v173
	v_mov_b32_e32 v174, 0xff800000
	v_mad_u32_u24 v0, v218, s37, v14
	v_lshl_add_u32 v215, v159, 1, v14
	ds_read_b128 v[220:223], v0
	ds_read_b128 v[236:239], v0 offset:4608
	ds_read_b128 v[224:227], v0 offset:32
	ds_read_b128 v[240:243], v0 offset:4640
	ds_read_b128 v[228:231], v0 offset:64
	ds_read_b128 v[244:247], v0 offset:4672
	ds_read_b128 v[232:235], v0 offset:96
	ds_read_b128 v[248:251], v0 offset:4704
	ds_read_b128 v[64:67], v215 offset:9216
	ds_read_b128 v[68:71], v215 offset:13824
	ds_read_b128 v[72:75], v215 offset:9248
	ds_read_b128 v[76:79], v215 offset:13856
	s_waitcnt lgkmcnt(11)
	v_mfma_f32_32x32x16_bf16 v[80:95], v[220:223], v[96:99], 0
	s_waitcnt lgkmcnt(10)
	v_mfma_f32_32x32x16_bf16 v[48:63], v[236:239], v[96:99], 0
	s_waitcnt lgkmcnt(9)
	v_mfma_f32_32x32x16_bf16 v[80:95], v[224:227], v[100:103], v[80:95]
	s_waitcnt lgkmcnt(8)
	v_mfma_f32_32x32x16_bf16 v[48:63], v[240:243], v[100:103], v[48:63]
	s_waitcnt lgkmcnt(7)
	v_mfma_f32_32x32x16_bf16 v[80:95], v[228:231], v[104:107], v[80:95]
	s_waitcnt lgkmcnt(6)
	v_mfma_f32_32x32x16_bf16 v[48:63], v[244:247], v[104:107], v[48:63]
	s_waitcnt lgkmcnt(5)
	v_mfma_f32_32x32x16_bf16 v[80:95], v[232:235], v[108:111], v[80:95]
	s_waitcnt lgkmcnt(4)
	v_mfma_f32_32x32x16_bf16 v[48:63], v[248:251], v[108:111], v[48:63]
	ds_read_b128 v[220:223], v215 offset:9280
	ds_read_b128 v[224:227], v215 offset:13888
	ds_read_b128 v[228:231], v215 offset:9312
	ds_read_b128 v[232:235], v215 offset:13920
	s_nop 7
	s_nop 3
	v_cmp_gt_i32_e64 vcc, 0, v173
	v_cmp_gt_i32_e64 s[4:5], 1, v173
	v_cmp_gt_i32_e64 s[6:7], 2, v173
	v_cndmask_b32_e32 v80, v174, v80, vcc
	v_cmp_gt_i32_e64 vcc, 3, v173
	v_cndmask_b32_e64 v81, v174, v81, s[4:5]
	v_cmp_gt_i32_e64 s[4:5], 4, v173
	v_cndmask_b32_e64 v82, v174, v82, s[6:7]
	v_cmp_gt_i32_e64 s[6:7], 5, v173
	v_cndmask_b32_e32 v83, v174, v83, vcc
	v_cmp_gt_i32_e64 vcc, 6, v173
	v_cndmask_b32_e64 v84, v174, v84, s[4:5]
	v_cmp_gt_i32_e64 s[4:5], 7, v173
	v_cndmask_b32_e64 v85, v174, v85, s[6:7]
	v_cmp_gt_i32_e64 s[6:7], 16, v173
	v_cndmask_b32_e32 v86, v174, v86, vcc
	v_cmp_gt_i32_e64 vcc, 17, v173
	v_cndmask_b32_e64 v87, v174, v87, s[4:5]
	v_cmp_gt_i32_e64 s[4:5], 18, v173
	v_cndmask_b32_e64 v88, v174, v88, s[6:7]
	v_cmp_gt_i32_e64 s[6:7], 19, v173
	v_cndmask_b32_e32 v89, v174, v89, vcc
	v_cmp_gt_i32_e64 vcc, 20, v173
	v_cndmask_b32_e64 v90, v174, v90, s[4:5]
	v_cmp_gt_i32_e64 s[4:5], 21, v173
	v_cndmask_b32_e64 v91, v174, v91, s[6:7]
	v_cmp_gt_i32_e64 s[6:7], 22, v173
	v_cndmask_b32_e32 v92, v174, v92, vcc
	v_cmp_gt_i32_e64 vcc, 23, v173
	v_cndmask_b32_e64 v93, v174, v93, s[4:5]
	v_cmp_gt_i32_e64 s[4:5], 0, v213
	v_cndmask_b32_e64 v94, v174, v94, s[6:7]
	v_cmp_gt_i32_e64 s[6:7], 1, v213
	v_cndmask_b32_e32 v95, v174, v95, vcc
	v_cmp_gt_i32_e64 vcc, 2, v213
	v_cndmask_b32_e64 v48, v174, v48, s[4:5]
	v_cmp_gt_i32_e64 s[4:5], 3, v213
	v_cndmask_b32_e64 v49, v174, v49, s[6:7]
	v_cmp_gt_i32_e64 s[6:7], 4, v213
	v_cndmask_b32_e32 v50, v174, v50, vcc
	v_cmp_gt_i32_e64 vcc, 5, v213
	v_cndmask_b32_e64 v51, v174, v51, s[4:5]
	v_cmp_gt_i32_e64 s[4:5], 6, v213
	v_cndmask_b32_e64 v52, v174, v52, s[6:7]
	v_cmp_gt_i32_e64 s[6:7], 7, v213
	v_cndmask_b32_e32 v53, v174, v53, vcc
	v_cmp_gt_i32_e64 vcc, 16, v213
	v_cndmask_b32_e64 v54, v174, v54, s[4:5]
	v_cmp_gt_i32_e64 s[4:5], 17, v213
	v_cndmask_b32_e64 v55, v174, v55, s[6:7]
	v_cmp_gt_i32_e64 s[6:7], 18, v213
	v_cndmask_b32_e32 v56, v174, v56, vcc
	v_cmp_gt_i32_e64 vcc, 19, v213
	v_cndmask_b32_e64 v57, v174, v57, s[4:5]
	v_cmp_gt_i32_e64 s[4:5], 20, v213
	v_cndmask_b32_e64 v58, v174, v58, s[6:7]
	v_cmp_gt_i32_e64 s[6:7], 21, v213
	v_cndmask_b32_e32 v59, v174, v59, vcc
	v_cmp_gt_i32_e64 vcc, 22, v213
	v_cndmask_b32_e64 v60, v174, v60, s[4:5]
	v_cmp_gt_i32_e64 s[4:5], 23, v213
	v_cndmask_b32_e64 v61, v174, v61, s[6:7]
	s_nop 0
	v_cndmask_b32_e32 v62, v174, v62, vcc
	s_nop 0
	v_cndmask_b32_e64 v63, v174, v63, s[4:5]
	s_nop 0
	v_max3_f32 v0, v80, v81, v82
	v_max3_f32 v216, v88, v89, v90
	v_max3_f32 v0, v0, v83, v84
	v_max3_f32 v216, v216, v91, v92
	v_max3_f32 v0, v0, v85, v86
	v_max3_f32 v216, v216, v93, v94
	v_max3_f32 v0, v0, v87, v95
	v_max_f32_e32 v0, v0, v216
	v_max3_f32 v175, v48, v49, v50
	v_max3_f32 v214, v56, v57, v58
	v_max3_f32 v175, v175, v51, v52
	v_max3_f32 v214, v214, v59, v60
	v_max3_f32 v175, v175, v53, v54
	v_max3_f32 v214, v214, v61, v62
	v_max3_f32 v175, v175, v55, v63
	v_max_f32_e32 v175, v175, v214
	v_cmp_gt_f32_e32 vcc, v0, v219
	s_cmp_eq_u64 vcc, 0
	s_cbranch_scc1 .Lnsw1el_keep0
	s_nop 0
	ds_bpermute_b32 v216, v119, v0
	s_waitcnt lgkmcnt(0)
	v_max_f32_e32 v0, v0, v216
	v_max_f32_e32 v173, v168, v0
	v_sub_f32_e32 v0, v168, v173
	v_exp_f32_e32 v0, v0
	v_mov_b32_e32 v168, v173
	v_add_f32_e32 v219, 0x41200000, v173
	v_mul_f32_e32 v169, v169, v0
	v_pk_mul_f32 v[46:47], v[46:47], v[0:1] op_sel_hi:[1,0]
	v_pk_mul_f32 v[44:45], v[44:45], v[0:1] op_sel_hi:[1,0]
	v_pk_mul_f32 v[42:43], v[42:43], v[0:1] op_sel_hi:[1,0]
	v_pk_mul_f32 v[40:41], v[40:41], v[0:1] op_sel_hi:[1,0]
	v_pk_mul_f32 v[38:39], v[38:39], v[0:1] op_sel_hi:[1,0]
	v_pk_mul_f32 v[36:37], v[36:37], v[0:1] op_sel_hi:[1,0]
	v_pk_mul_f32 v[34:35], v[34:35], v[0:1] op_sel_hi:[1,0]
	v_pk_mul_f32 v[32:33], v[32:33], v[0:1] op_sel_hi:[1,0]
	v_pk_mul_f32 v[30:31], v[30:31], v[0:1] op_sel_hi:[1,0]
	v_pk_mul_f32 v[28:29], v[28:29], v[0:1] op_sel_hi:[1,0]
	v_pk_mul_f32 v[26:27], v[26:27], v[0:1] op_sel_hi:[1,0]
	v_pk_mul_f32 v[24:25], v[24:25], v[0:1] op_sel_hi:[1,0]
	v_pk_mul_f32 v[22:23], v[22:23], v[0:1] op_sel_hi:[1,0]
	v_pk_mul_f32 v[20:21], v[20:21], v[0:1] op_sel_hi:[1,0]
	v_pk_mul_f32 v[18:19], v[18:19], v[0:1] op_sel_hi:[1,0]
	v_pk_mul_f32 v[16:17], v[16:17], v[0:1] op_sel_hi:[1,0]

.LBB0_307:
	v_mad_u32_u24 v0, v218, s37, v14
	v_lshl_add_u32 v215, v159, 1, v14
	ds_read_b128 v[220:223], v0
	ds_read_b128 v[236:239], v0 offset:4608
	ds_read_b128 v[224:227], v0 offset:32
	ds_read_b128 v[240:243], v0 offset:4640
	ds_read_b128 v[228:231], v0 offset:64
	ds_read_b128 v[244:247], v0 offset:4672
	ds_read_b128 v[232:235], v0 offset:96
	ds_read_b128 v[248:251], v0 offset:4704
	ds_read_b128 v[64:67], v215 offset:9216
	ds_read_b128 v[68:71], v215 offset:13824
	ds_read_b128 v[72:75], v215 offset:9248
	ds_read_b128 v[76:79], v215 offset:13856
	s_waitcnt lgkmcnt(11)
	v_mfma_f32_32x32x16_bf16 v[80:95], v[220:223], v[96:99], 0
	s_waitcnt lgkmcnt(10)
	v_mfma_f32_32x32x16_bf16 v[48:63], v[236:239], v[96:99], 0
	s_waitcnt lgkmcnt(9)
	v_mfma_f32_32x32x16_bf16 v[80:95], v[224:227], v[100:103], v[80:95]
	s_waitcnt lgkmcnt(8)
	v_mfma_f32_32x32x16_bf16 v[48:63], v[240:243], v[100:103], v[48:63]
	s_waitcnt lgkmcnt(7)
	v_mfma_f32_32x32x16_bf16 v[80:95], v[228:231], v[104:107], v[80:95]
	s_waitcnt lgkmcnt(6)
	v_mfma_f32_32x32x16_bf16 v[48:63], v[244:247], v[104:107], v[48:63]
	s_waitcnt lgkmcnt(5)
	v_mfma_f32_32x32x16_bf16 v[80:95], v[232:235], v[108:111], v[80:95]
	s_waitcnt lgkmcnt(4)
	v_mfma_f32_32x32x16_bf16 v[48:63], v[248:251], v[108:111], v[48:63]
	ds_read_b128 v[220:223], v215 offset:9280
	ds_read_b128 v[224:227], v215 offset:13888
	ds_read_b128 v[228:231], v215 offset:9312
	ds_read_b128 v[232:235], v215 offset:13920
	s_nop 7
	v_max3_f32 v0, v80, v81, v82
	v_max3_f32 v216, v88, v89, v90
	v_max3_f32 v0, v0, v83, v84
	v_max3_f32 v216, v216, v91, v92
	v_max3_f32 v0, v0, v85, v86
	v_max3_f32 v216, v216, v93, v94
	v_max3_f32 v0, v0, v87, v95
	v_max_f32_e32 v0, v0, v216
	v_max3_f32 v175, v48, v49, v50
	v_max3_f32 v214, v56, v57, v58
	v_max3_f32 v175, v175, v51, v52
	v_max3_f32 v214, v214, v59, v60
	v_max3_f32 v175, v175, v53, v54
	v_max3_f32 v214, v214, v61, v62
	v_max3_f32 v175, v175, v55, v63
	v_max_f32_e32 v175, v175, v214
	v_cmp_gt_f32_e32 vcc, v0, v219
	s_cmp_eq_u64 vcc, 0
	s_cbranch_scc1 .Lnsw1_keep0
	s_nop 0
	ds_bpermute_b32 v216, v119, v0
	s_waitcnt lgkmcnt(0)
	v_max_f32_e32 v0, v0, v216
	v_max_f32_e32 v173, v168, v0
	v_sub_f32_e32 v0, v168, v173
	v_exp_f32_e32 v0, v0
	v_mov_b32_e32 v168, v173
	v_add_f32_e32 v219, 0x41200000, v173
	v_mul_f32_e32 v169, v169, v0
	v_pk_mul_f32 v[46:47], v[46:47], v[0:1] op_sel_hi:[1,0]
	v_pk_mul_f32 v[44:45], v[44:45], v[0:1] op_sel_hi:[1,0]
	v_pk_mul_f32 v[42:43], v[42:43], v[0:1] op_sel_hi:[1,0]
	v_pk_mul_f32 v[40:41], v[40:41], v[0:1] op_sel_hi:[1,0]
	v_pk_mul_f32 v[38:39], v[38:39], v[0:1] op_sel_hi:[1,0]
	v_pk_mul_f32 v[36:37], v[36:37], v[0:1] op_sel_hi:[1,0]
	v_pk_mul_f32 v[34:35], v[34:35], v[0:1] op_sel_hi:[1,0]
	v_pk_mul_f32 v[32:33], v[32:33], v[0:1] op_sel_hi:[1,0]
	v_pk_mul_f32 v[30:31], v[30:31], v[0:1] op_sel_hi:[1,0]
	v_pk_mul_f32 v[28:29], v[28:29], v[0:1] op_sel_hi:[1,0]
	v_pk_mul_f32 v[26:27], v[26:27], v[0:1] op_sel_hi:[1,0]
	v_pk_mul_f32 v[24:25], v[24:25], v[0:1] op_sel_hi:[1,0]
	v_pk_mul_f32 v[22:23], v[22:23], v[0:1] op_sel_hi:[1,0]
	v_pk_mul_f32 v[20:21], v[20:21], v[0:1] op_sel_hi:[1,0]
	v_pk_mul_f32 v[18:19], v[18:19], v[0:1] op_sel_hi:[1,0]
	v_pk_mul_f32 v[16:17], v[16:17], v[0:1] op_sel_hi:[1,0]

.Lnsw1_keep1:
	v_sub_f32_e32 v48, v48, v168
	v_exp_f32_e32 v48, v48
	v_sub_f32_e32 v49, v49, v168
	v_exp_f32_e32 v49, v49
	v_sub_f32_e32 v50, v50, v168
	v_exp_f32_e32 v50, v50
	v_add_f32_e32 v213, v49, v48
	v_sub_f32_e32 v51, v51, v168
	v_exp_f32_e32 v51, v51
	v_add_f32_e32 v213, v50, v213
	v_cvt_pk_bf16_f32 v80, v48, v49
	v_sub_f32_e32 v52, v52, v168
	v_exp_f32_e32 v52, v52
	v_add_f32_e32 v213, v51, v213
	v_sub_f32_e32 v53, v53, v168
	v_exp_f32_e32 v53, v53
	v_add_f32_e32 v213, v52, v213
	v_cvt_pk_bf16_f32 v81, v50, v51
	v_sub_f32_e32 v54, v54, v168
	v_exp_f32_e32 v54, v54
	v_add_f32_e32 v213, v53, v213
	v_sub_f32_e32 v55, v55, v168
	v_exp_f32_e32 v55, v55
	v_add_f32_e32 v213, v54, v213
	v_cvt_pk_bf16_f32 v82, v52, v53
	v_sub_f32_e32 v56, v56, v168
	v_exp_f32_e32 v56, v56
	v_add_f32_e32 v213, v55, v213
	v_sub_f32_e32 v57, v57, v168
	v_exp_f32_e32 v57, v57
	v_add_f32_e32 v213, v56, v213
	v_cvt_pk_bf16_f32 v83, v54, v55
	v_sub_f32_e32 v58, v58, v168
	v_exp_f32_e32 v58, v58
	v_add_f32_e32 v213, v57, v213
	s_waitcnt lgkmcnt(3)
	v_mfma_f32_32x32x16_bf16 v[32:47], v[220:223], v[80:83], v[32:47]
	s_waitcnt lgkmcnt(2)
	v_mfma_f32_32x32x16_bf16 v[16:31], v[224:227], v[80:83], v[16:31]
	v_sub_f32_e32 v59, v59, v168
	v_exp_f32_e32 v59, v59
	v_add_f32_e32 v213, v58, v213
	v_cvt_pk_bf16_f32 v84, v56, v57
	v_sub_f32_e32 v60, v60, v168
	v_exp_f32_e32 v60, v60
	v_add_f32_e32 v213, v59, v213
	v_sub_f32_e32 v61, v61, v168
	v_exp_f32_e32 v61, v61
	v_add_f32_e32 v213, v60, v213
	v_cvt_pk_bf16_f32 v85, v58, v59
	v_sub_f32_e32 v62, v62, v168
	v_exp_f32_e32 v62, v62
	v_add_f32_e32 v213, v61, v213
	v_sub_f32_e32 v63, v63, v168
	v_exp_f32_e32 v63, v63
	v_add_f32_e32 v213, v62, v213
	v_cvt_pk_bf16_f32 v86, v60, v61
	v_add_f32_e32 v213, v63, v213
	v_cvt_pk_bf16_f32 v87, v62, v63
	v_add_f32_e32 v169, v169, v213
	s_nop 0
	s_waitcnt lgkmcnt(1)
	v_mfma_f32_32x32x16_bf16 v[32:47], v[228:231], v[84:87], v[32:47]
	s_waitcnt lgkmcnt(0)
	v_mfma_f32_32x32x16_bf16 v[16:31], v[232:235], v[84:87], v[16:31]
	s_branch .LBB0_314
.LBB0_314:
	s_xor_b32 s4, s14, 1
	s_mulk_i32 s4, 0x4800
	v_lshl_add_u32 v0, v158, 1, s4
	s_waitcnt vmcnt(3)
	ds_write_b128 v0, v[6:9]
	v_lshl_add_u32 v6, v160, 1, s4
	s_cmp_lt_i32 s12, s10
	s_waitcnt vmcnt(2)
	ds_write_b128 v6, v[2:5]
	s_waitcnt vmcnt(1)
	ds_write_b128 v0, v[10:13] offset:9216
	s_waitcnt vmcnt(0)
	ds_write_b128 v6, v[112:115] offset:9216
	s_waitcnt lgkmcnt(0)
	s_barrier
	s_cbranch_scc0 .Lnsw1_exit
	s_mov_b32 s12, s13
	s_branch .LBB0_301
